# v35: v22 with GEMM K-loop priorities swapped: load sections at s_setprio 1, MFMA sections at 0
# baseline (speedup 1.0000x reference)
; #define G_STAGE(bufoff, gbase, voff) do { _Pragma("unroll") for (int _i = 0; _i < 2; ++_i) \
;     __builtin_amdgcn_global_load_lds((const unsigned*)((const char*)(gbase) + (voff)[_i]), (LAS unsigned*)(lds + (bufoff) + ldsw + _i * 8192), 16, 0, 0); } while (0)
; #define G_LDA(dst, b, h) do { _Pragma("unroll") for (int m = 0; m < 4; ++m) _Pragma("unroll") for (int k = 0; k < 2; ++k) dst[m][k] = *(const LAS bf16x8*)(lds + G_SA(b, h) + aoff + m * 2048 + k * 1024); } while (0)
; #define G_LDB(dst, b, h) do { _Pragma("unroll") for (int n = 0; n < 2; ++n) _Pragma("unroll") for (int k = 0; k < 2; ++k) dst[n][k] = *(const LAS bf16x8*)(lds + G_SB(b, h) + boff + n * 2048 + k * 1024); } while (0)
; #define G_MMA(ai, bj, At, Bt) do { __builtin_amdgcn_s_setprio(1); _Pragma("unroll") for (int m = 0; m < 4; ++m) _Pragma("unroll") for (int n = 0; n < 2; ++n) _Pragma("unroll") for (int k = 0; k < 2; ++k) \
;     acc[ai][bj][m][n] = __builtin_amdgcn_mfma_f32_16x16x32_bf16(Bt[n][k], At[m][k], acc[ai][bj][m][n], 0, 0, 0); __builtin_amdgcn_s_setprio(0); } while (0)
; #define G_WAIT_L(n) asm volatile("s_waitcnt lgkmcnt(" #n ")" ::: "memory")
; #define G_BAR __builtin_amdgcn_s_barrier()
; #define G_SCHED __builtin_amdgcn_sched_barrier(0)
; template <int GP> DI void gemm_phase(const Params& p, int l, int which, char* smem, int wv) {
;     ...
;     for (int t = 0; t < cnk; t += 2) {
;       const bool last = (t == cnk - 2);
;       const char* a1 = cA + (size_t)(t + 1) * kstep;
;       const char* a2 = last ? nA : cA + (size_t)(t + 2) * kstep; const char* b2 = last ? nB : cB + (size_t)(t + 2) * kstep;
;       const char* a3 = a2 + kstep; const char* b3 = b2 + kstep;
;       if (last) {
; #pragma unroll
;         for (int i = 0; i < 2; ++i) { vb0[i] = voffB(i, 0, n32); vb1[i] = voffB(i, 1, n32); }
;       }
;       G_LDB(B0, 0, 0); G_SCHED; G_LDA(At, 0, 0); G_STAGE(G_SA(1, 1), a1 + hstep, voffA);
;       G_WAIT_L(8); G_BAR; G_WAIT_L(0); G_MMA(0, 0, At, B0); G_BAR; G_SCHED;
;       G_LDB(B1, 0, 1); G_STAGE(G_SB(0, 0), b2, vb0);
;       G_BAR; G_WAIT_L(0); G_MMA(0, 1, At, B1); G_BAR;
;       G_LDA(At, 0, 1); G_STAGE(G_SA(0, 0), a2, voffA);
;       G_BAR; G_WAIT_L(0); G_MMA(1, 0, At, B0); G_BAR; G_SCHED;
.LBB0_149:
	v_add_u32_e32 v135, 0x10000, v166
	s_add_u32 s61, s8, s26
	ds_read_b128 v[168:171], v135
	ds_read_b128 v[172:175], v135 offset:1024
	ds_read_b128 v[176:179], v135 offset:2048
	ds_read_b128 v[180:183], v135 offset:3072
	s_addc_u32 s62, s9, s27
	s_and_b64 s[30:31], s[28:29], exec
	s_cselect_b32 s31, s11, s62
	s_cselect_b32 s30, s57, s61
	s_add_u32 s61, s6, s26
	s_addc_u32 s62, s7, s27
	s_and_b64 s[28:29], s[28:29], exec
	s_cselect_b32 s28, s59, s61
	s_cselect_b32 s29, s58, s62
	s_mov_b32 m0, s53
	v_lshl_add_u64 v[216:217], s[8:9], 0, v[162:163]
	ds_read_b128 v[184:187], v165
	ds_read_b128 v[188:191], v165 offset:1024
	ds_read_b128 v[192:195], v165 offset:2048
	ds_read_b128 v[196:199], v165 offset:3072
	ds_read_b128 v[200:203], v165 offset:4096
	ds_read_b128 v[204:207], v165 offset:5120
	ds_read_b128 v[208:211], v165 offset:6144
	ds_read_b128 v[212:215], v165 offset:7168
	global_load_lds_dwordx4 v[216:217], off
	v_lshl_add_u64 v[216:217], s[8:9], 0, v[160:161]
	s_mov_b32 m0, s54
	s_nop 0
	global_load_lds_dwordx4 v[216:217], off
	s_waitcnt lgkmcnt(8)
	s_barrier
	s_waitcnt lgkmcnt(0)
	s_setprio 0
	s_waitcnt lgkmcnt(0)
	v_mfma_f32_16x16x32_bf16 v[62:65], v[168:171], v[184:187], v[62:65]
	v_mfma_f32_16x16x32_bf16 v[58:61], v[176:179], v[184:187], v[58:61]
	v_mfma_f32_16x16x32_bf16 v[54:57], v[168:171], v[192:195], v[54:57]
	v_mfma_f32_16x16x32_bf16 v[50:53], v[176:179], v[192:195], v[50:53]
	v_mfma_f32_16x16x32_bf16 v[46:49], v[168:171], v[200:203], v[46:49]
	v_mfma_f32_16x16x32_bf16 v[42:45], v[176:179], v[200:203], v[42:45]
	v_mfma_f32_16x16x32_bf16 v[38:41], v[168:171], v[208:211], v[38:41]
	v_mfma_f32_16x16x32_bf16 v[34:37], v[176:179], v[208:211], v[34:37]
	v_mfma_f32_16x16x32_bf16 v[62:65], v[172:175], v[188:191], v[62:65]
	v_mfma_f32_16x16x32_bf16 v[58:61], v[180:183], v[188:191], v[58:61]
	v_mfma_f32_16x16x32_bf16 v[54:57], v[172:175], v[196:199], v[54:57]
	v_mfma_f32_16x16x32_bf16 v[50:53], v[180:183], v[196:199], v[50:53]
	v_mfma_f32_16x16x32_bf16 v[46:49], v[172:175], v[204:207], v[46:49]
	v_mfma_f32_16x16x32_bf16 v[42:45], v[180:183], v[204:207], v[42:45]
	v_mfma_f32_16x16x32_bf16 v[38:41], v[172:175], v[212:215], v[38:41]
	v_mfma_f32_16x16x32_bf16 v[34:37], v[180:183], v[212:215], v[34:37]
	s_setprio 1
	s_barrier
	s_mov_b32 m0, s1
	v_add_u32_e32 v135, 0x14000, v166
	ds_read_b128 v[216:219], v135
	ds_read_b128 v[220:223], v135 offset:1024
	ds_read_b128 v[224:227], v135 offset:2048
	ds_read_b128 v[238:241], v135 offset:3072
	global_load_lds_dwordx4 v0, s[28:29]
	s_mov_b32 m0, s3
	v_mov_b32_e32 v137, v1
	global_load_lds_dwordx4 v136, s[28:29]
	s_barrier
	s_waitcnt lgkmcnt(0)
	v_lshl_add_u64 v[228:229], s[28:29], 0, v[0:1]
	v_lshl_add_u64 v[234:235], s[28:29], 0, v[136:137]
	s_setprio 0
	s_waitcnt lgkmcnt(0)
	v_mfma_f32_16x16x32_bf16 v[30:33], v[216:219], v[184:187], v[30:33]
	v_mfma_f32_16x16x32_bf16 v[26:29], v[224:227], v[184:187], v[26:29]
	v_mfma_f32_16x16x32_bf16 v[22:25], v[216:219], v[192:195], v[22:25]
	v_mfma_f32_16x16x32_bf16 v[18:21], v[224:227], v[192:195], v[18:21]
	v_mfma_f32_16x16x32_bf16 v[14:17], v[216:219], v[200:203], v[14:17]
	v_mfma_f32_16x16x32_bf16 v[10:13], v[224:227], v[200:203], v[10:13]
	v_mfma_f32_16x16x32_bf16 v[6:9], v[216:219], v[208:211], v[6:9]
	v_mfma_f32_16x16x32_bf16 v[2:5], v[224:227], v[208:211], v[2:5]
	v_mfma_f32_16x16x32_bf16 v[30:33], v[220:223], v[188:191], v[30:33]
	v_mfma_f32_16x16x32_bf16 v[26:29], v[238:241], v[188:191], v[26:29]
	v_mfma_f32_16x16x32_bf16 v[22:25], v[220:223], v[196:199], v[22:25]
	v_mfma_f32_16x16x32_bf16 v[18:21], v[238:241], v[196:199], v[18:21]
	v_mfma_f32_16x16x32_bf16 v[14:17], v[220:223], v[204:207], v[14:17]
	v_mfma_f32_16x16x32_bf16 v[10:13], v[238:241], v[204:207], v[10:13]
	v_mfma_f32_16x16x32_bf16 v[6:9], v[220:223], v[212:215], v[6:9]
	v_mfma_f32_16x16x32_bf16 v[2:5], v[238:241], v[212:215], v[2:5]
	s_setprio 1
	s_mov_b32 m0, s38
	v_lshl_add_u64 v[242:243], s[30:31], 0, v[130:131]
	s_barrier
	ds_read_b128 v[184:187], v165 offset:16384
	ds_read_b128 v[188:191], v165 offset:17408
	ds_read_b128 v[192:195], v165 offset:18432
	ds_read_b128 v[196:199], v165 offset:19456
	ds_read_b128 v[200:203], v165 offset:20480
	ds_read_b128 v[204:207], v165 offset:21504
	ds_read_b128 v[208:211], v165 offset:22528
	ds_read_b128 v[212:215], v165 offset:23552
	global_load_lds_dwordx4 v[242:243], off
	v_lshl_add_u64 v[244:245], s[30:31], 0, v[132:133]
	s_mov_b32 m0, s5
	s_nop 0
	global_load_lds_dwordx4 v[244:245], off
	s_barrier
	s_waitcnt lgkmcnt(0)
	s_setprio 0
	s_waitcnt lgkmcnt(0)
	v_mfma_f32_16x16x32_bf16 v[66:69], v[168:171], v[184:187], v[66:69]
	v_mfma_f32_16x16x32_bf16 v[70:73], v[176:179], v[184:187], v[70:73]
	v_mfma_f32_16x16x32_bf16 v[74:77], v[168:171], v[192:195], v[74:77]
	v_mfma_f32_16x16x32_bf16 v[78:81], v[176:179], v[192:195], v[78:81]
	v_mfma_f32_16x16x32_bf16 v[82:85], v[168:171], v[200:203], v[82:85]
	v_mfma_f32_16x16x32_bf16 v[86:89], v[176:179], v[200:203], v[86:89]
	v_mfma_f32_16x16x32_bf16 v[90:93], v[168:171], v[208:211], v[90:93]
	v_mfma_f32_16x16x32_bf16 v[98:101], v[176:179], v[208:211], v[98:101]
	v_mfma_f32_16x16x32_bf16 v[66:69], v[172:175], v[188:191], v[66:69]
	v_mfma_f32_16x16x32_bf16 v[70:73], v[180:183], v[188:191], v[70:73]
	v_mfma_f32_16x16x32_bf16 v[74:77], v[172:175], v[196:199], v[74:77]
	v_mfma_f32_16x16x32_bf16 v[78:81], v[180:183], v[196:199], v[78:81]
	v_mfma_f32_16x16x32_bf16 v[82:85], v[172:175], v[204:207], v[82:85]
	v_mfma_f32_16x16x32_bf16 v[86:89], v[180:183], v[204:207], v[86:89]
	v_mfma_f32_16x16x32_bf16 v[90:93], v[172:175], v[212:215], v[90:93]
	v_mfma_f32_16x16x32_bf16 v[98:101], v[180:183], v[212:215], v[98:101]
	s_setprio 1
	s_barrier
; #define G_STAGE(bufoff, gbase, voff) do { _Pragma("unroll") for (int _i = 0; _i < 2; ++_i) \
;     __builtin_amdgcn_global_load_lds((const unsigned*)((const char*)(gbase) + (voff)[_i]), (LAS unsigned*)(lds + (bufoff) + ldsw + _i * 8192), 16, 0, 0); } while (0)
; #define G_LDA(dst, b, h) do { _Pragma("unroll") for (int m = 0; m < 4; ++m) _Pragma("unroll") for (int k = 0; k < 2; ++k) dst[m][k] = *(const LAS bf16x8*)(lds + G_SA(b, h) + aoff + m * 2048 + k * 1024); } while (0)
; #define G_LDB(dst, b, h) do { _Pragma("unroll") for (int n = 0; n < 2; ++n) _Pragma("unroll") for (int k = 0; k < 2; ++k) dst[n][k] = *(const LAS bf16x8*)(lds + G_SB(b, h) + boff + n * 2048 + k * 1024); } while (0)
; #define G_MMA(ai, bj, At, Bt) do { __builtin_amdgcn_s_setprio(1); _Pragma("unroll") for (int m = 0; m < 4; ++m) _Pragma("unroll") for (int n = 0; n < 2; ++n) _Pragma("unroll") for (int k = 0; k < 2; ++k) \
;     acc[ai][bj][m][n] = __builtin_amdgcn_mfma_f32_16x16x32_bf16(Bt[n][k], At[m][k], acc[ai][bj][m][n], 0, 0, 0); __builtin_amdgcn_s_setprio(0); } while (0)
; #define G_WAIT_V(n) asm volatile("s_waitcnt vmcnt(" #n ")" ::: "memory")
; #define G_WAIT_L(n) asm volatile("s_waitcnt lgkmcnt(" #n ")" ::: "memory")
; #define G_BAR __builtin_amdgcn_s_barrier()
; #define G_SCHED __builtin_amdgcn_sched_barrier(0)
; template <int GP> DI void gemm_phase(const Params& p, int l, int which, char* smem, int wv) {
;     ...
;       G_STAGE(G_SB(0, 1), b2, vb1);
;       G_WAIT_V(6); G_BAR; G_MMA(1, 1, At, B1); G_BAR;
;       G_LDB(B0, 1, 0); G_SCHED; G_LDA(At, 1, 0); G_STAGE(G_SA(0, 1), a2 + hstep, voffA);
;       G_WAIT_L(8); G_BAR; G_WAIT_L(0); G_MMA(0, 0, At, B0); G_BAR; G_SCHED;
;       G_LDB(B1, 1, 1); G_STAGE(G_SB(1, 0), b3, vb0);
	s_mov_b32 m0, s41
	v_mov_b32_e32 v135, v1
	global_load_lds_dwordx4 v134, s[28:29]
	s_mov_b32 m0, s42
	v_mov_b32_e32 v155, v1
	global_load_lds_dwordx4 v154, s[28:29]
	s_waitcnt vmcnt(6)
	v_lshl_add_u64 v[246:247], s[28:29], 0, v[134:135]
	v_lshl_add_u64 v[248:249], s[28:29], 0, v[154:155]
	s_barrier
	s_setprio 0
	v_mfma_f32_16x16x32_bf16 v[94:97], v[216:219], v[184:187], v[94:97]
	v_mfma_f32_16x16x32_bf16 v[102:105], v[224:227], v[184:187], v[102:105]
	v_mfma_f32_16x16x32_bf16 v[106:109], v[216:219], v[192:195], v[106:109]
	v_mfma_f32_16x16x32_bf16 v[110:113], v[224:227], v[192:195], v[110:113]
	v_mfma_f32_16x16x32_bf16 v[114:117], v[216:219], v[200:203], v[114:117]
	v_mfma_f32_16x16x32_bf16 v[118:121], v[224:227], v[200:203], v[118:121]
	v_mfma_f32_16x16x32_bf16 v[122:125], v[216:219], v[208:211], v[122:125]
	v_mfma_f32_16x16x32_bf16 v[126:129], v[224:227], v[208:211], v[126:129]
	v_mfma_f32_16x16x32_bf16 v[94:97], v[220:223], v[188:191], v[94:97]
	v_mfma_f32_16x16x32_bf16 v[102:105], v[238:241], v[188:191], v[102:105]
	v_mfma_f32_16x16x32_bf16 v[106:109], v[220:223], v[196:199], v[106:109]
	v_mfma_f32_16x16x32_bf16 v[110:113], v[238:241], v[196:199], v[110:113]
	v_mfma_f32_16x16x32_bf16 v[114:117], v[220:223], v[204:207], v[114:117]
	v_mfma_f32_16x16x32_bf16 v[118:121], v[238:241], v[204:207], v[118:121]
	v_mfma_f32_16x16x32_bf16 v[122:125], v[220:223], v[212:215], v[122:125]
	v_mfma_f32_16x16x32_bf16 v[126:129], v[238:241], v[212:215], v[126:129]
	s_setprio 1
	v_add_u32_e32 v135, 0x18000, v166
	s_barrier
	ds_read_b128 v[168:171], v135
	ds_read_b128 v[172:175], v135 offset:1024
	ds_read_b128 v[176:179], v135 offset:2048
	ds_read_b128 v[180:183], v135 offset:3072
	s_add_u32 s28, s30, 0x80000
	s_addc_u32 s29, s31, 0
	s_mov_b32 m0, s43
	v_lshl_add_u64 v[216:217], s[28:29], 0, v[130:131]
	ds_read_b128 v[184:187], v165 offset:32768
	ds_read_b128 v[188:191], v165 offset:33792
	ds_read_b128 v[192:195], v165 offset:34816
	ds_read_b128 v[196:199], v165 offset:35840
	ds_read_b128 v[200:203], v165 offset:36864
	ds_read_b128 v[204:207], v165 offset:37888
	ds_read_b128 v[208:211], v165 offset:38912
	ds_read_b128 v[212:215], v165 offset:39936
	global_load_lds_dwordx4 v[216:217], off
	v_lshl_add_u64 v[216:217], s[28:29], 0, v[132:133]
	s_mov_b32 m0, s44
	s_nop 0
	global_load_lds_dwordx4 v[216:217], off
	s_waitcnt lgkmcnt(8)
	s_barrier
	s_waitcnt lgkmcnt(0)
	s_setprio 0
	s_waitcnt lgkmcnt(0)
	v_mfma_f32_16x16x32_bf16 v[62:65], v[168:171], v[184:187], v[62:65]
	v_mfma_f32_16x16x32_bf16 v[58:61], v[176:179], v[184:187], v[58:61]
	v_mfma_f32_16x16x32_bf16 v[54:57], v[168:171], v[192:195], v[54:57]
	v_mfma_f32_16x16x32_bf16 v[50:53], v[176:179], v[192:195], v[50:53]
	v_mfma_f32_16x16x32_bf16 v[46:49], v[168:171], v[200:203], v[46:49]
	v_mfma_f32_16x16x32_bf16 v[42:45], v[176:179], v[200:203], v[42:45]
	v_mfma_f32_16x16x32_bf16 v[38:41], v[168:171], v[208:211], v[38:41]
	v_mfma_f32_16x16x32_bf16 v[34:37], v[176:179], v[208:211], v[34:37]
	v_mfma_f32_16x16x32_bf16 v[62:65], v[172:175], v[188:191], v[62:65]
	v_mfma_f32_16x16x32_bf16 v[58:61], v[180:183], v[188:191], v[58:61]
	v_mfma_f32_16x16x32_bf16 v[54:57], v[172:175], v[196:199], v[54:57]
	v_mfma_f32_16x16x32_bf16 v[50:53], v[180:183], v[196:199], v[50:53]
	v_mfma_f32_16x16x32_bf16 v[46:49], v[172:175], v[204:207], v[46:49]
	v_mfma_f32_16x16x32_bf16 v[42:45], v[180:183], v[204:207], v[42:45]
	v_mfma_f32_16x16x32_bf16 v[38:41], v[172:175], v[212:215], v[38:41]
	v_mfma_f32_16x16x32_bf16 v[34:37], v[180:183], v[212:215], v[34:37]
	s_setprio 1
	s_barrier
	s_mov_b32 m0, s45
	v_add_u32_e32 v135, 0x1c000, v166
	v_lshl_add_u64 v[228:229], v[228:229], 0, s[74:75]
	ds_read_b128 v[216:219], v135
	ds_read_b128 v[220:223], v135 offset:1024
	ds_read_b128 v[224:227], v135 offset:2048
	ds_read_b128 v[238:241], v135 offset:3072
	global_load_lds_dwordx4 v[228:229], off
	v_lshl_add_u64 v[228:229], v[234:235], 0, s[74:75]
	s_mov_b32 m0, s46
	s_nop 0
	global_load_lds_dwordx4 v[228:229], off
	s_barrier
; #define G_STAGE(bufoff, gbase, voff) do { _Pragma("unroll") for (int _i = 0; _i < 2; ++_i) \
;     __builtin_amdgcn_global_load_lds((const unsigned*)((const char*)(gbase) + (voff)[_i]), (LAS unsigned*)(lds + (bufoff) + ldsw + _i * 8192), 16, 0, 0); } while (0)
; #define G_LDA(dst, b, h) do { _Pragma("unroll") for (int m = 0; m < 4; ++m) _Pragma("unroll") for (int k = 0; k < 2; ++k) dst[m][k] = *(const LAS bf16x8*)(lds + G_SA(b, h) + aoff + m * 2048 + k * 1024); } while (0)
; #define G_MMA(ai, bj, At, Bt) do { __builtin_amdgcn_s_setprio(1); _Pragma("unroll") for (int m = 0; m < 4; ++m) _Pragma("unroll") for (int n = 0; n < 2; ++n) _Pragma("unroll") for (int k = 0; k < 2; ++k) \
;     acc[ai][bj][m][n] = __builtin_amdgcn_mfma_f32_16x16x32_bf16(Bt[n][k], At[m][k], acc[ai][bj][m][n], 0, 0, 0); __builtin_amdgcn_s_setprio(0); } while (0)
; #define G_WAIT_V(n) asm volatile("s_waitcnt vmcnt(" #n ")" ::: "memory")
; #define G_WAIT_L(n) asm volatile("s_waitcnt lgkmcnt(" #n ")" ::: "memory")
; #define G_BAR __builtin_amdgcn_s_barrier()
; #define G_SCHED __builtin_amdgcn_sched_barrier(0)
; template <int GP> DI void gemm_phase(const Params& p, int l, int which, char* smem, int wv) {
;     ...
;       G_BAR; G_WAIT_L(0); G_MMA(0, 1, At, B1); G_BAR;
;       G_LDA(At, 1, 1); G_STAGE(G_SA(1, 0), a3, voffA);
;       G_BAR; G_WAIT_L(0); G_MMA(1, 0, At, B0); G_BAR; G_SCHED;
;       G_STAGE(G_SB(1, 1), b3, vb1);
;       G_WAIT_V(6); G_BAR; G_MMA(1, 1, At, B1); G_BAR;
;     }
;     if (GP == 0) {
;       const int m0 = cmt * 256, n0 = cnt_ * 256;
;       const bool isctx = (cmt % 9) == 0;
;       const int head = wc >> 1;
;       const int n128 = cnt_ * 2 + head;
;       const int rowl0 = wr * 64 + fr;
;       if (which) {
;         const int colb = n0 + head * 128 + (wc & 1) * 32 + fq * 8;
;         u16* ybase = isctx ? p.ypart + ((size_t)(ck0 >> 8) * 1024 + (size_t)(cmt / 9) * 256) * DM : p.y + (size_t)m0 * DM;
	s_waitcnt lgkmcnt(0)
	s_setprio 0
	s_waitcnt lgkmcnt(0)
	v_mfma_f32_16x16x32_bf16 v[30:33], v[216:219], v[184:187], v[30:33]
	v_mfma_f32_16x16x32_bf16 v[26:29], v[224:227], v[184:187], v[26:29]
	v_mfma_f32_16x16x32_bf16 v[22:25], v[216:219], v[192:195], v[22:25]
	v_mfma_f32_16x16x32_bf16 v[18:21], v[224:227], v[192:195], v[18:21]
	v_mfma_f32_16x16x32_bf16 v[14:17], v[216:219], v[200:203], v[14:17]
	v_mfma_f32_16x16x32_bf16 v[10:13], v[224:227], v[200:203], v[10:13]
	v_mfma_f32_16x16x32_bf16 v[6:9], v[216:219], v[208:211], v[6:9]
	v_mfma_f32_16x16x32_bf16 v[2:5], v[224:227], v[208:211], v[2:5]
	v_mfma_f32_16x16x32_bf16 v[30:33], v[220:223], v[188:191], v[30:33]
	v_mfma_f32_16x16x32_bf16 v[26:29], v[238:241], v[188:191], v[26:29]
	v_mfma_f32_16x16x32_bf16 v[22:25], v[220:223], v[196:199], v[22:25]
	v_mfma_f32_16x16x32_bf16 v[18:21], v[238:241], v[196:199], v[18:21]
	v_mfma_f32_16x16x32_bf16 v[14:17], v[220:223], v[204:207], v[14:17]
	v_mfma_f32_16x16x32_bf16 v[10:13], v[238:241], v[204:207], v[10:13]
	v_mfma_f32_16x16x32_bf16 v[6:9], v[220:223], v[212:215], v[6:9]
	v_mfma_f32_16x16x32_bf16 v[2:5], v[238:241], v[212:215], v[2:5]
	s_setprio 1
	s_mov_b32 m0, s48
	v_lshl_add_u64 v[228:229], v[242:243], 0, s[74:75]
	s_barrier
	ds_read_b128 v[184:187], v165 offset:49152
	ds_read_b128 v[188:191], v165 offset:50176
	ds_read_b128 v[192:195], v165 offset:51200
	ds_read_b128 v[196:199], v165 offset:52224
	ds_read_b128 v[200:203], v165 offset:53248
	ds_read_b128 v[204:207], v165 offset:54272
	ds_read_b128 v[208:211], v165 offset:55296
	ds_read_b128 v[212:215], v165 offset:56320
	global_load_lds_dwordx4 v[228:229], off
	v_lshl_add_u64 v[228:229], v[244:245], 0, s[74:75]
	s_mov_b32 m0, s49
	s_nop 0
	global_load_lds_dwordx4 v[228:229], off
	s_barrier
	s_waitcnt lgkmcnt(0)
	s_setprio 0
	s_waitcnt lgkmcnt(0)
	v_mfma_f32_16x16x32_bf16 v[66:69], v[168:171], v[184:187], v[66:69]
	v_mfma_f32_16x16x32_bf16 v[70:73], v[176:179], v[184:187], v[70:73]
	v_mfma_f32_16x16x32_bf16 v[74:77], v[168:171], v[192:195], v[74:77]
	v_mfma_f32_16x16x32_bf16 v[78:81], v[176:179], v[192:195], v[78:81]
	v_mfma_f32_16x16x32_bf16 v[82:85], v[168:171], v[200:203], v[82:85]
	v_mfma_f32_16x16x32_bf16 v[86:89], v[176:179], v[200:203], v[86:89]
	v_mfma_f32_16x16x32_bf16 v[90:93], v[168:171], v[208:211], v[90:93]
	v_mfma_f32_16x16x32_bf16 v[98:101], v[176:179], v[208:211], v[98:101]
	v_mfma_f32_16x16x32_bf16 v[66:69], v[172:175], v[188:191], v[66:69]
	v_mfma_f32_16x16x32_bf16 v[70:73], v[180:183], v[188:191], v[70:73]
	v_mfma_f32_16x16x32_bf16 v[74:77], v[172:175], v[196:199], v[74:77]
	v_mfma_f32_16x16x32_bf16 v[78:81], v[180:183], v[196:199], v[78:81]
	v_mfma_f32_16x16x32_bf16 v[82:85], v[172:175], v[204:207], v[82:85]
	v_mfma_f32_16x16x32_bf16 v[86:89], v[180:183], v[204:207], v[86:89]
	v_mfma_f32_16x16x32_bf16 v[90:93], v[172:175], v[212:215], v[90:93]
	v_mfma_f32_16x16x32_bf16 v[98:101], v[180:183], v[212:215], v[98:101]
	s_setprio 1
	s_barrier
	s_mov_b32 m0, s50
	v_lshl_add_u64 v[168:169], v[246:247], 0, s[74:75]
	global_load_lds_dwordx4 v[168:169], off
	v_lshl_add_u64 v[168:169], v[248:249], 0, s[74:75]
	s_mov_b32 m0, s52
	s_nop 0
	global_load_lds_dwordx4 v[168:169], off
	s_waitcnt vmcnt(6)
	s_barrier
	s_setprio 0
	v_mfma_f32_16x16x32_bf16 v[94:97], v[216:219], v[184:187], v[94:97]
	v_mfma_f32_16x16x32_bf16 v[102:105], v[224:227], v[184:187], v[102:105]
	v_mfma_f32_16x16x32_bf16 v[106:109], v[216:219], v[192:195], v[106:109]
	v_mfma_f32_16x16x32_bf16 v[110:113], v[224:227], v[192:195], v[110:113]
	v_mfma_f32_16x16x32_bf16 v[114:117], v[216:219], v[200:203], v[114:117]
	v_mfma_f32_16x16x32_bf16 v[118:121], v[224:227], v[200:203], v[118:121]
	v_mfma_f32_16x16x32_bf16 v[122:125], v[216:219], v[208:211], v[122:125]
	v_mfma_f32_16x16x32_bf16 v[126:129], v[224:227], v[208:211], v[126:129]
	v_mfma_f32_16x16x32_bf16 v[94:97], v[220:223], v[188:191], v[94:97]
	v_mfma_f32_16x16x32_bf16 v[102:105], v[238:241], v[188:191], v[102:105]
	v_mfma_f32_16x16x32_bf16 v[106:109], v[220:223], v[196:199], v[106:109]
	v_mfma_f32_16x16x32_bf16 v[110:113], v[238:241], v[196:199], v[110:113]
	v_mfma_f32_16x16x32_bf16 v[114:117], v[220:223], v[204:207], v[114:117]
	v_mfma_f32_16x16x32_bf16 v[118:121], v[238:241], v[204:207], v[118:121]
	v_mfma_f32_16x16x32_bf16 v[122:125], v[220:223], v[212:215], v[122:125]
	v_mfma_f32_16x16x32_bf16 v[126:129], v[238:241], v[212:215], v[126:129]
	s_setprio 1
	s_add_i32 s28, s60, 2
	s_add_u32 s26, s26, 0x100
	s_addc_u32 s27, s27, 0
	v_lshl_add_u64 v[162:163], v[162:163], 0, s[78:79]
	s_cmp_ge_i32 s60, s36
	v_lshl_add_u64 v[160:161], v[160:161], 0, s[78:79]
	s_barrier
	s_cbranch_scc0 .LBB0_147
	s_setprio 0
	s_mul_hi_i32 s11, s2, 0x38e38e39
	s_lshr_b32 s26, s11, 31
	s_ashr_i32 s11, s11, 1
	s_add_i32 s26, s11, s26
	s_mul_i32 s11, s26, 9
	s_sub_i32 s11, s2, s11
	s_cmp_lg_u32 s11, 0
	s_cbranch_scc0 .LBB0_155
	s_lshl_b32 s28, s2, 8
	s_ashr_i32 s29, s28, 31
	s_lshl_b64 s[28:29], s[28:29], 12
	s_add_u32 s28, s94, s28
	s_addc_u32 s29, s95, s29
	s_cbranch_execnz .LBB0_153

; #define G_STAGE(bufoff, gbase, voff) do { _Pragma("unroll") for (int _i = 0; _i < 2; ++_i) \
;     __builtin_amdgcn_global_load_lds((const unsigned*)((const char*)(gbase) + (voff)[_i]), (LAS unsigned*)(lds + (bufoff) + ldsw + _i * 8192), 16, 0, 0); } while (0)
; #define G_LDA(dst, b, h) do { _Pragma("unroll") for (int m = 0; m < 4; ++m) _Pragma("unroll") for (int k = 0; k < 2; ++k) dst[m][k] = *(const LAS bf16x8*)(lds + G_SA(b, h) + aoff + m * 2048 + k * 1024); } while (0)
; #define G_LDB(dst, b, h) do { _Pragma("unroll") for (int n = 0; n < 2; ++n) _Pragma("unroll") for (int k = 0; k < 2; ++k) dst[n][k] = *(const LAS bf16x8*)(lds + G_SB(b, h) + boff + n * 2048 + k * 1024); } while (0)
; #define G_MMA(ai, bj, At, Bt) do { __builtin_amdgcn_s_setprio(1); _Pragma("unroll") for (int m = 0; m < 4; ++m) _Pragma("unroll") for (int n = 0; n < 2; ++n) _Pragma("unroll") for (int k = 0; k < 2; ++k) \
;     acc[ai][bj][m][n] = __builtin_amdgcn_mfma_f32_16x16x32_bf16(Bt[n][k], At[m][k], acc[ai][bj][m][n], 0, 0, 0); __builtin_amdgcn_s_setprio(0); } while (0)
; #define G_WAIT_L(n) asm volatile("s_waitcnt lgkmcnt(" #n ")" ::: "memory")
; #define G_BAR __builtin_amdgcn_s_barrier()
; #define G_SCHED __builtin_amdgcn_sched_barrier(0)
; template <int GP> DI void gemm_phase(const Params& p, int l, int which, char* smem, int wv) {
;     ...
;     for (int t = 0; t < cnk; t += 2) {
;       const bool last = (t == cnk - 2);
;       const char* a1 = cA + (size_t)(t + 1) * kstep;
;       const char* a2 = last ? nA : cA + (size_t)(t + 2) * kstep; const char* b2 = last ? nB : cB + (size_t)(t + 2) * kstep;
;       const char* a3 = a2 + kstep; const char* b3 = b2 + kstep;
;       if (last) {
; #pragma unroll
;         for (int i = 0; i < 2; ++i) { vb0[i] = voffB(i, 0, n32); vb1[i] = voffB(i, 1, n32); }
;       }
;       G_LDB(B0, 0, 0); G_SCHED; G_LDA(At, 0, 0); G_STAGE(G_SA(1, 1), a1 + hstep, voffA);
;       G_WAIT_L(8); G_BAR; G_WAIT_L(0); G_MMA(0, 0, At, B0); G_BAR; G_SCHED;
;       G_LDB(B1, 0, 1); G_STAGE(G_SB(0, 0), b2, vb0);
;       G_BAR; G_WAIT_L(0); G_MMA(0, 1, At, B1); G_BAR;
;       G_LDA(At, 0, 1); G_STAGE(G_SA(0, 0), a2, voffA);
;       G_BAR; G_WAIT_L(0); G_MMA(1, 0, At, B0); G_BAR; G_SCHED;
.LBB0_209:
	s_add_u32 s8, s28, s2
	v_add_u32_e32 v131, 0x10000, v212
	s_addc_u32 s9, s29, s3
	ds_read_b128 v[148:151], v131
	ds_read_b128 v[152:155], v131 offset:1024
	ds_read_b128 v[156:159], v131 offset:2048
	ds_read_b128 v[160:163], v131 offset:3072
	s_add_u32 s52, s8, 0x100
	s_addc_u32 s53, s9, 0
	s_and_b64 s[8:9], s[6:7], exec
	s_cselect_b32 s9, s10, s53
	s_cselect_b32 s8, s11, s52
	s_add_u32 s52, s74, s2
	s_addc_u32 s53, s75, s3
	s_and_b64 s[6:7], s[6:7], exec
	s_cselect_b32 s7, s37, s53
	s_cselect_b32 s6, s39, s52
	v_lshl_add_u64 v[196:197], v[144:145], 0, s[2:3]
	s_add_i32 m0, s23, 0xc000
	ds_read_b128 v[164:167], v211
	ds_read_b128 v[168:171], v211 offset:1024
	ds_read_b128 v[172:175], v211 offset:2048
	ds_read_b128 v[176:179], v211 offset:3072
	ds_read_b128 v[180:183], v211 offset:4096
	ds_read_b128 v[184:187], v211 offset:5120
	ds_read_b128 v[188:191], v211 offset:6144
	ds_read_b128 v[192:195], v211 offset:7168
	global_load_lds_dwordx4 v[196:197], off
	v_lshl_add_u64 v[196:197], v[146:147], 0, s[2:3]
	s_add_i32 m0, s23, 0xe000
	s_nop 0
	global_load_lds_dwordx4 v[196:197], off
	s_waitcnt lgkmcnt(8)
	s_barrier
	s_waitcnt lgkmcnt(0)
	s_setprio 0
	s_waitcnt lgkmcnt(0)
	v_mfma_f32_16x16x32_bf16 v[62:65], v[148:151], v[164:167], v[62:65]
	v_mfma_f32_16x16x32_bf16 v[58:61], v[156:159], v[164:167], v[58:61]
	v_mfma_f32_16x16x32_bf16 v[54:57], v[148:151], v[172:175], v[54:57]
	v_mfma_f32_16x16x32_bf16 v[50:53], v[156:159], v[172:175], v[50:53]
	v_mfma_f32_16x16x32_bf16 v[46:49], v[148:151], v[180:183], v[46:49]
	v_mfma_f32_16x16x32_bf16 v[42:45], v[156:159], v[180:183], v[42:45]
	v_mfma_f32_16x16x32_bf16 v[38:41], v[148:151], v[188:191], v[38:41]
	v_mfma_f32_16x16x32_bf16 v[34:37], v[156:159], v[188:191], v[34:37]
	v_mfma_f32_16x16x32_bf16 v[62:65], v[152:155], v[168:171], v[62:65]
	v_mfma_f32_16x16x32_bf16 v[58:61], v[160:163], v[168:171], v[58:61]
	v_mfma_f32_16x16x32_bf16 v[54:57], v[152:155], v[176:179], v[54:57]
	v_mfma_f32_16x16x32_bf16 v[50:53], v[160:163], v[176:179], v[50:53]
	v_mfma_f32_16x16x32_bf16 v[46:49], v[152:155], v[184:187], v[46:49]
	v_mfma_f32_16x16x32_bf16 v[42:45], v[160:163], v[184:187], v[42:45]
	v_mfma_f32_16x16x32_bf16 v[38:41], v[152:155], v[192:195], v[38:41]
	v_mfma_f32_16x16x32_bf16 v[34:37], v[160:163], v[192:195], v[34:37]
	s_setprio 1
	s_barrier
	s_mov_b32 m0, s25
	v_add_u32_e32 v131, 0x14000, v212
	ds_read_b128 v[196:199], v131
	ds_read_b128 v[200:203], v131 offset:1024
	ds_read_b128 v[204:207], v131 offset:2048
	ds_read_b128 v[238:241], v131 offset:3072
	global_load_lds_dwordx4 v0, s[6:7]
	s_mov_b32 m0, s58
	v_mov_b32_e32 v137, v1
	global_load_lds_dwordx4 v136, s[6:7]
	s_barrier
	s_waitcnt lgkmcnt(0)
	v_lshl_add_u64 v[228:229], s[6:7], 0, v[0:1]
	v_lshl_add_u64 v[234:235], s[6:7], 0, v[136:137]
	s_setprio 0
	s_waitcnt lgkmcnt(0)
	v_mfma_f32_16x16x32_bf16 v[30:33], v[196:199], v[164:167], v[30:33]
	v_mfma_f32_16x16x32_bf16 v[26:29], v[204:207], v[164:167], v[26:29]
	v_mfma_f32_16x16x32_bf16 v[22:25], v[196:199], v[172:175], v[22:25]
	v_mfma_f32_16x16x32_bf16 v[18:21], v[204:207], v[172:175], v[18:21]
	v_mfma_f32_16x16x32_bf16 v[14:17], v[196:199], v[180:183], v[14:17]
	v_mfma_f32_16x16x32_bf16 v[10:13], v[204:207], v[180:183], v[10:13]
	v_mfma_f32_16x16x32_bf16 v[6:9], v[196:199], v[188:191], v[6:9]
	v_mfma_f32_16x16x32_bf16 v[2:5], v[204:207], v[188:191], v[2:5]
	v_mfma_f32_16x16x32_bf16 v[30:33], v[200:203], v[168:171], v[30:33]
	v_mfma_f32_16x16x32_bf16 v[26:29], v[238:241], v[168:171], v[26:29]
	v_mfma_f32_16x16x32_bf16 v[22:25], v[200:203], v[176:179], v[22:25]
	v_mfma_f32_16x16x32_bf16 v[18:21], v[238:241], v[176:179], v[18:21]
	v_mfma_f32_16x16x32_bf16 v[14:17], v[200:203], v[184:187], v[14:17]
	v_mfma_f32_16x16x32_bf16 v[10:13], v[238:241], v[184:187], v[10:13]
	v_mfma_f32_16x16x32_bf16 v[6:9], v[200:203], v[192:195], v[6:9]
	v_mfma_f32_16x16x32_bf16 v[2:5], v[238:241], v[192:195], v[2:5]
	s_setprio 1
	s_mov_b32 m0, s23
	v_lshl_add_u64 v[242:243], s[8:9], 0, v[132:133]
	s_barrier
	ds_read_b128 v[164:167], v211 offset:16384
	ds_read_b128 v[168:171], v211 offset:17408
	ds_read_b128 v[172:175], v211 offset:18432
	ds_read_b128 v[176:179], v211 offset:19456
	ds_read_b128 v[180:183], v211 offset:20480
	ds_read_b128 v[184:187], v211 offset:21504
	ds_read_b128 v[188:191], v211 offset:22528
	ds_read_b128 v[192:195], v211 offset:23552
	global_load_lds_dwordx4 v[242:243], off
	v_lshl_add_u64 v[244:245], s[8:9], 0, v[134:135]
	s_mov_b32 m0, s59
	s_nop 0
	global_load_lds_dwordx4 v[244:245], off
	s_barrier
	s_waitcnt lgkmcnt(0)
	s_setprio 0
	s_waitcnt lgkmcnt(0)
	v_mfma_f32_16x16x32_bf16 v[66:69], v[148:151], v[164:167], v[66:69]
	v_mfma_f32_16x16x32_bf16 v[70:73], v[156:159], v[164:167], v[70:73]
	v_mfma_f32_16x16x32_bf16 v[74:77], v[148:151], v[172:175], v[74:77]
	v_mfma_f32_16x16x32_bf16 v[78:81], v[156:159], v[172:175], v[78:81]
	v_mfma_f32_16x16x32_bf16 v[82:85], v[148:151], v[180:183], v[82:85]
	v_mfma_f32_16x16x32_bf16 v[86:89], v[156:159], v[180:183], v[86:89]
	v_mfma_f32_16x16x32_bf16 v[90:93], v[148:151], v[188:191], v[90:93]
	v_mfma_f32_16x16x32_bf16 v[94:97], v[156:159], v[188:191], v[94:97]
	v_mfma_f32_16x16x32_bf16 v[66:69], v[152:155], v[168:171], v[66:69]
	v_mfma_f32_16x16x32_bf16 v[70:73], v[160:163], v[168:171], v[70:73]
	v_mfma_f32_16x16x32_bf16 v[74:77], v[152:155], v[176:179], v[74:77]
	v_mfma_f32_16x16x32_bf16 v[78:81], v[160:163], v[176:179], v[78:81]
	v_mfma_f32_16x16x32_bf16 v[82:85], v[152:155], v[184:187], v[82:85]
	v_mfma_f32_16x16x32_bf16 v[86:89], v[160:163], v[184:187], v[86:89]
	v_mfma_f32_16x16x32_bf16 v[90:93], v[152:155], v[192:195], v[90:93]
	v_mfma_f32_16x16x32_bf16 v[94:97], v[160:163], v[192:195], v[94:97]
	s_setprio 1
	s_barrier
; #define G_STAGE(bufoff, gbase, voff) do { _Pragma("unroll") for (int _i = 0; _i < 2; ++_i) \
;     __builtin_amdgcn_global_load_lds((const unsigned*)((const char*)(gbase) + (voff)[_i]), (LAS unsigned*)(lds + (bufoff) + ldsw + _i * 8192), 16, 0, 0); } while (0)
; #define G_LDA(dst, b, h) do { _Pragma("unroll") for (int m = 0; m < 4; ++m) _Pragma("unroll") for (int k = 0; k < 2; ++k) dst[m][k] = *(const LAS bf16x8*)(lds + G_SA(b, h) + aoff + m * 2048 + k * 1024); } while (0)
; #define G_LDB(dst, b, h) do { _Pragma("unroll") for (int n = 0; n < 2; ++n) _Pragma("unroll") for (int k = 0; k < 2; ++k) dst[n][k] = *(const LAS bf16x8*)(lds + G_SB(b, h) + boff + n * 2048 + k * 1024); } while (0)
; #define G_MMA(ai, bj, At, Bt) do { __builtin_amdgcn_s_setprio(1); _Pragma("unroll") for (int m = 0; m < 4; ++m) _Pragma("unroll") for (int n = 0; n < 2; ++n) _Pragma("unroll") for (int k = 0; k < 2; ++k) \
;     acc[ai][bj][m][n] = __builtin_amdgcn_mfma_f32_16x16x32_bf16(Bt[n][k], At[m][k], acc[ai][bj][m][n], 0, 0, 0); __builtin_amdgcn_s_setprio(0); } while (0)
; #define G_WAIT_V(n) asm volatile("s_waitcnt vmcnt(" #n ")" ::: "memory")
; #define G_WAIT_L(n) asm volatile("s_waitcnt lgkmcnt(" #n ")" ::: "memory")
; #define G_BAR __builtin_amdgcn_s_barrier()
; #define G_SCHED __builtin_amdgcn_sched_barrier(0)
; template <int GP> DI void gemm_phase(const Params& p, int l, int which, char* smem, int wv) {
;     ...
;       G_STAGE(G_SB(0, 1), b2, vb1);
;       G_WAIT_V(6); G_BAR; G_MMA(1, 1, At, B1); G_BAR;
;       G_LDB(B0, 1, 0); G_SCHED; G_LDA(At, 1, 0); G_STAGE(G_SA(0, 1), a2 + hstep, voffA);
;       G_WAIT_L(8); G_BAR; G_WAIT_L(0); G_MMA(0, 0, At, B0); G_BAR; G_SCHED;
;       G_LDB(B1, 1, 1); G_STAGE(G_SB(1, 0), b3, vb0);
	s_mov_b32 m0, s60
	v_mov_b32_e32 v131, v1
	global_load_lds_dwordx4 v130, s[6:7]
	s_mov_b32 m0, s61
	v_mov_b32_e32 v143, v1
	global_load_lds_dwordx4 v142, s[6:7]
	s_waitcnt vmcnt(6)
	v_lshl_add_u64 v[246:247], s[6:7], 0, v[130:131]
	v_lshl_add_u64 v[248:249], s[6:7], 0, v[142:143]
	s_barrier
	s_setprio 0
	v_mfma_f32_16x16x32_bf16 v[98:101], v[196:199], v[164:167], v[98:101]
	v_mfma_f32_16x16x32_bf16 v[102:105], v[204:207], v[164:167], v[102:105]
	v_mfma_f32_16x16x32_bf16 v[106:109], v[196:199], v[172:175], v[106:109]
	v_mfma_f32_16x16x32_bf16 v[110:113], v[204:207], v[172:175], v[110:113]
	v_mfma_f32_16x16x32_bf16 v[114:117], v[196:199], v[180:183], v[114:117]
	v_mfma_f32_16x16x32_bf16 v[118:121], v[204:207], v[180:183], v[118:121]
	v_mfma_f32_16x16x32_bf16 v[122:125], v[196:199], v[188:191], v[122:125]
	v_mfma_f32_16x16x32_bf16 v[126:129], v[204:207], v[188:191], v[126:129]
	v_mfma_f32_16x16x32_bf16 v[98:101], v[200:203], v[168:171], v[98:101]
	v_mfma_f32_16x16x32_bf16 v[102:105], v[238:241], v[168:171], v[102:105]
	v_mfma_f32_16x16x32_bf16 v[106:109], v[200:203], v[176:179], v[106:109]
	v_mfma_f32_16x16x32_bf16 v[110:113], v[238:241], v[176:179], v[110:113]
	v_mfma_f32_16x16x32_bf16 v[114:117], v[200:203], v[184:187], v[114:117]
	v_mfma_f32_16x16x32_bf16 v[118:121], v[238:241], v[184:187], v[118:121]
	v_mfma_f32_16x16x32_bf16 v[122:125], v[200:203], v[192:195], v[122:125]
	v_mfma_f32_16x16x32_bf16 v[126:129], v[238:241], v[192:195], v[126:129]
	s_setprio 1
	v_add_u32_e32 v131, 0x18000, v212
	s_barrier
	ds_read_b128 v[148:151], v131
	ds_read_b128 v[152:155], v131 offset:1024
	ds_read_b128 v[156:159], v131 offset:2048
	ds_read_b128 v[160:163], v131 offset:3072
	s_add_u32 s6, s8, 0x80000
	s_addc_u32 s7, s9, 0
	s_mov_b32 m0, s62
	v_lshl_add_u64 v[196:197], s[6:7], 0, v[132:133]
	ds_read_b128 v[164:167], v211 offset:32768
	ds_read_b128 v[168:171], v211 offset:33792
	ds_read_b128 v[172:175], v211 offset:34816
	ds_read_b128 v[176:179], v211 offset:35840
	ds_read_b128 v[180:183], v211 offset:36864
	ds_read_b128 v[184:187], v211 offset:37888
	ds_read_b128 v[188:191], v211 offset:38912
	ds_read_b128 v[192:195], v211 offset:39936
	global_load_lds_dwordx4 v[196:197], off
	v_lshl_add_u64 v[196:197], s[6:7], 0, v[134:135]
	s_mov_b32 m0, s63
	s_nop 0
	global_load_lds_dwordx4 v[196:197], off
	s_waitcnt lgkmcnt(8)
	s_barrier
	s_waitcnt lgkmcnt(0)
	s_setprio 0
	s_waitcnt lgkmcnt(0)
	v_mfma_f32_16x16x32_bf16 v[62:65], v[148:151], v[164:167], v[62:65]
	v_mfma_f32_16x16x32_bf16 v[58:61], v[156:159], v[164:167], v[58:61]
	v_mfma_f32_16x16x32_bf16 v[54:57], v[148:151], v[172:175], v[54:57]
	v_mfma_f32_16x16x32_bf16 v[50:53], v[156:159], v[172:175], v[50:53]
	v_mfma_f32_16x16x32_bf16 v[46:49], v[148:151], v[180:183], v[46:49]
	v_mfma_f32_16x16x32_bf16 v[42:45], v[156:159], v[180:183], v[42:45]
	v_mfma_f32_16x16x32_bf16 v[38:41], v[148:151], v[188:191], v[38:41]
	v_mfma_f32_16x16x32_bf16 v[34:37], v[156:159], v[188:191], v[34:37]
	v_mfma_f32_16x16x32_bf16 v[62:65], v[152:155], v[168:171], v[62:65]
	v_mfma_f32_16x16x32_bf16 v[58:61], v[160:163], v[168:171], v[58:61]
	v_mfma_f32_16x16x32_bf16 v[54:57], v[152:155], v[176:179], v[54:57]
	v_mfma_f32_16x16x32_bf16 v[50:53], v[160:163], v[176:179], v[50:53]
	v_mfma_f32_16x16x32_bf16 v[46:49], v[152:155], v[184:187], v[46:49]
	v_mfma_f32_16x16x32_bf16 v[42:45], v[160:163], v[184:187], v[42:45]
	v_mfma_f32_16x16x32_bf16 v[38:41], v[152:155], v[192:195], v[38:41]
	v_mfma_f32_16x16x32_bf16 v[34:37], v[160:163], v[192:195], v[34:37]
	s_setprio 1
	s_barrier
	s_mov_b32 m0, s21
	v_add_u32_e32 v131, 0x1c000, v212
	v_lshl_add_u64 v[228:229], v[228:229], 0, s[16:17]
	ds_read_b128 v[196:199], v131
	ds_read_b128 v[200:203], v131 offset:1024
	ds_read_b128 v[204:207], v131 offset:2048
	ds_read_b128 v[238:241], v131 offset:3072
	global_load_lds_dwordx4 v[228:229], off
	v_lshl_add_u64 v[228:229], v[234:235], 0, s[16:17]
	s_mov_b32 m0, s64
	s_nop 0
	global_load_lds_dwordx4 v[228:229], off
	s_barrier
; #define G_STAGE(bufoff, gbase, voff) do { _Pragma("unroll") for (int _i = 0; _i < 2; ++_i) \
;     __builtin_amdgcn_global_load_lds((const unsigned*)((const char*)(gbase) + (voff)[_i]), (LAS unsigned*)(lds + (bufoff) + ldsw + _i * 8192), 16, 0, 0); } while (0)
; #define G_LDA(dst, b, h) do { _Pragma("unroll") for (int m = 0; m < 4; ++m) _Pragma("unroll") for (int k = 0; k < 2; ++k) dst[m][k] = *(const LAS bf16x8*)(lds + G_SA(b, h) + aoff + m * 2048 + k * 1024); } while (0)
; #define G_MMA(ai, bj, At, Bt) do { __builtin_amdgcn_s_setprio(1); _Pragma("unroll") for (int m = 0; m < 4; ++m) _Pragma("unroll") for (int n = 0; n < 2; ++n) _Pragma("unroll") for (int k = 0; k < 2; ++k) \
;     acc[ai][bj][m][n] = __builtin_amdgcn_mfma_f32_16x16x32_bf16(Bt[n][k], At[m][k], acc[ai][bj][m][n], 0, 0, 0); __builtin_amdgcn_s_setprio(0); } while (0)
; #define G_WAIT_V(n) asm volatile("s_waitcnt vmcnt(" #n ")" ::: "memory")
; #define G_WAIT_L(n) asm volatile("s_waitcnt lgkmcnt(" #n ")" ::: "memory")
; #define G_BAR __builtin_amdgcn_s_barrier()
; #define G_SCHED __builtin_amdgcn_sched_barrier(0)
; template <int GP> DI void gemm_phase(const Params& p, int l, int which, char* smem, int wv) {
;     ...
;       G_BAR; G_WAIT_L(0); G_MMA(0, 1, At, B1); G_BAR;
;       G_LDA(At, 1, 1); G_STAGE(G_SA(1, 0), a3, voffA);
;       G_BAR; G_WAIT_L(0); G_MMA(1, 0, At, B0); G_BAR; G_SCHED;
;       G_STAGE(G_SB(1, 1), b3, vb1);
;       G_WAIT_V(6); G_BAR; G_MMA(1, 1, At, B1); G_BAR;
;     }
	s_waitcnt lgkmcnt(0)
	s_setprio 0
	s_waitcnt lgkmcnt(0)
	v_mfma_f32_16x16x32_bf16 v[30:33], v[196:199], v[164:167], v[30:33]
	v_mfma_f32_16x16x32_bf16 v[26:29], v[204:207], v[164:167], v[26:29]
	v_mfma_f32_16x16x32_bf16 v[22:25], v[196:199], v[172:175], v[22:25]
	v_mfma_f32_16x16x32_bf16 v[18:21], v[204:207], v[172:175], v[18:21]
	v_mfma_f32_16x16x32_bf16 v[14:17], v[196:199], v[180:183], v[14:17]
	v_mfma_f32_16x16x32_bf16 v[10:13], v[204:207], v[180:183], v[10:13]
	v_mfma_f32_16x16x32_bf16 v[6:9], v[196:199], v[188:191], v[6:9]
	v_mfma_f32_16x16x32_bf16 v[2:5], v[204:207], v[188:191], v[2:5]
	v_mfma_f32_16x16x32_bf16 v[30:33], v[200:203], v[168:171], v[30:33]
	v_mfma_f32_16x16x32_bf16 v[26:29], v[238:241], v[168:171], v[26:29]
	v_mfma_f32_16x16x32_bf16 v[22:25], v[200:203], v[176:179], v[22:25]
	v_mfma_f32_16x16x32_bf16 v[18:21], v[238:241], v[176:179], v[18:21]
	v_mfma_f32_16x16x32_bf16 v[14:17], v[200:203], v[184:187], v[14:17]
	v_mfma_f32_16x16x32_bf16 v[10:13], v[238:241], v[184:187], v[10:13]
	v_mfma_f32_16x16x32_bf16 v[6:9], v[200:203], v[192:195], v[6:9]
	v_mfma_f32_16x16x32_bf16 v[2:5], v[238:241], v[192:195], v[2:5]
	s_setprio 1
	s_mov_b32 m0, s65
	v_lshl_add_u64 v[228:229], v[242:243], 0, s[16:17]
	s_barrier
	ds_read_b128 v[164:167], v211 offset:49152
	ds_read_b128 v[168:171], v211 offset:50176
	ds_read_b128 v[172:175], v211 offset:51200
	ds_read_b128 v[176:179], v211 offset:52224
	ds_read_b128 v[180:183], v211 offset:53248
	ds_read_b128 v[184:187], v211 offset:54272
	ds_read_b128 v[188:191], v211 offset:55296
	ds_read_b128 v[192:195], v211 offset:56320
	global_load_lds_dwordx4 v[228:229], off
	v_lshl_add_u64 v[228:229], v[244:245], 0, s[16:17]
	s_mov_b32 m0, s66
	s_nop 0
	global_load_lds_dwordx4 v[228:229], off
	s_barrier
	s_waitcnt lgkmcnt(0)
	s_setprio 0
	s_waitcnt lgkmcnt(0)
	v_mfma_f32_16x16x32_bf16 v[66:69], v[148:151], v[164:167], v[66:69]
	v_mfma_f32_16x16x32_bf16 v[70:73], v[156:159], v[164:167], v[70:73]
	v_mfma_f32_16x16x32_bf16 v[74:77], v[148:151], v[172:175], v[74:77]
	v_mfma_f32_16x16x32_bf16 v[78:81], v[156:159], v[172:175], v[78:81]
	v_mfma_f32_16x16x32_bf16 v[82:85], v[148:151], v[180:183], v[82:85]
	v_mfma_f32_16x16x32_bf16 v[86:89], v[156:159], v[180:183], v[86:89]
	v_mfma_f32_16x16x32_bf16 v[90:93], v[148:151], v[188:191], v[90:93]
	v_mfma_f32_16x16x32_bf16 v[94:97], v[156:159], v[188:191], v[94:97]
	v_mfma_f32_16x16x32_bf16 v[66:69], v[152:155], v[168:171], v[66:69]
	v_mfma_f32_16x16x32_bf16 v[70:73], v[160:163], v[168:171], v[70:73]
	v_mfma_f32_16x16x32_bf16 v[74:77], v[152:155], v[176:179], v[74:77]
	v_mfma_f32_16x16x32_bf16 v[78:81], v[160:163], v[176:179], v[78:81]
	v_mfma_f32_16x16x32_bf16 v[82:85], v[152:155], v[184:187], v[82:85]
	v_mfma_f32_16x16x32_bf16 v[86:89], v[160:163], v[184:187], v[86:89]
	v_mfma_f32_16x16x32_bf16 v[90:93], v[152:155], v[192:195], v[90:93]
	v_mfma_f32_16x16x32_bf16 v[94:97], v[160:163], v[192:195], v[94:97]
	s_setprio 1
	s_barrier
	s_mov_b32 m0, s67
	v_lshl_add_u64 v[148:149], v[246:247], 0, s[16:17]
	global_load_lds_dwordx4 v[148:149], off
	v_lshl_add_u64 v[148:149], v[248:249], 0, s[16:17]
	s_mov_b32 m0, s68
	s_nop 0
	global_load_lds_dwordx4 v[148:149], off
	s_waitcnt vmcnt(6)
	s_barrier
	s_setprio 0
	v_mfma_f32_16x16x32_bf16 v[98:101], v[196:199], v[164:167], v[98:101]
	v_mfma_f32_16x16x32_bf16 v[102:105], v[204:207], v[164:167], v[102:105]
	v_mfma_f32_16x16x32_bf16 v[106:109], v[196:199], v[172:175], v[106:109]
	v_mfma_f32_16x16x32_bf16 v[110:113], v[204:207], v[172:175], v[110:113]
	v_mfma_f32_16x16x32_bf16 v[114:117], v[196:199], v[180:183], v[114:117]
	v_mfma_f32_16x16x32_bf16 v[118:121], v[204:207], v[180:183], v[118:121]
	v_mfma_f32_16x16x32_bf16 v[122:125], v[196:199], v[188:191], v[122:125]
	v_mfma_f32_16x16x32_bf16 v[126:129], v[204:207], v[188:191], v[126:129]
	v_mfma_f32_16x16x32_bf16 v[98:101], v[200:203], v[168:171], v[98:101]
	v_mfma_f32_16x16x32_bf16 v[102:105], v[238:241], v[168:171], v[102:105]
	v_mfma_f32_16x16x32_bf16 v[106:109], v[200:203], v[176:179], v[106:109]
	v_mfma_f32_16x16x32_bf16 v[110:113], v[238:241], v[176:179], v[110:113]
	v_mfma_f32_16x16x32_bf16 v[114:117], v[200:203], v[184:187], v[114:117]
	v_mfma_f32_16x16x32_bf16 v[118:121], v[238:241], v[184:187], v[118:121]
	v_mfma_f32_16x16x32_bf16 v[122:125], v[200:203], v[192:195], v[122:125]
	v_mfma_f32_16x16x32_bf16 v[126:129], v[238:241], v[192:195], v[126:129]
	s_setprio 1
	s_add_i32 s50, s50, 2
	s_add_u32 s2, s2, 0x100
	s_addc_u32 s3, s3, 0
	s_cmp_gt_u32 s50, 29
	s_barrier
	s_cbranch_scc1 .LBB0_219

; template <int GP> DI void gemm_phase(const Params& p, int l, int which, char* smem, int wv) {
;     ...
;         int hh = 64; bool rope = false, silu = false; float qmul = 1.f; const float* ng = nullptr;
;         if (n128 < 4) { hh = 32; rope = true; qmul = 0.125f * LOG2E; }
;         else if (n128 < 8) { hh = 32; rope = true; }
;         else if (n128 < 12) { }
;         else if (n128 < 16) { rope = true; qmul = 0.08838834764831845f * LOG2E; }
;         else if (n128 < 18) { rope = true; }
;         else if (n128 < 20) { }
;         else if (n128 < 24) { qmul = 0.08838834764831845f * LOG2E; }
;         else if (n128 < 32) { }
;         else if (n128 < 36) { rope = true; qmul = 0.08838834764831845f * LOG2E; ng = p.gq + l * 128; }
;         else if (n128 < 38) { rope = true; ng = p.gk + l * 128; }
;         else if (n128 < 40) { }
;         else { silu = true; }
.LBB0_219:
	s_setprio 0
	s_lshl_b32 s2, s24, 1
	s_or_b32 s0, s2, s69
	s_cmp_gt_i32 s0, 3
	s_cbranch_scc0 .LBB0_230
	s_cmp_lt_u32 s2, 8
	s_cbranch_scc1 .LBB0_232
	s_cmp_lt_u32 s2, 12
	s_cbranch_scc1 .LBB0_233
	s_cmp_lt_u32 s2, 16
	s_cbranch_scc1 .LBB0_235
	s_cmp_lt_u32 s2, 18
	s_cbranch_scc1 .LBB0_236
	s_cmp_lt_u32 s2, 20
	s_cbranch_scc1 .LBB0_233
	s_cmp_lt_u32 s2, 24
	s_cbranch_scc1 .LBB0_352
	s_cmp_lt_u32 s2, 32
	s_cbranch_scc1 .LBB0_233
	s_cmp_lt_u32 s2, 36
	s_cbranch_scc1 .LBB0_353
	s_cmp_lt_u32 s2, 38
	s_cbranch_scc1 .LBB0_354
	s_cmp_gt_u32 s2, 39
	s_mov_b64 s[0:1], 0
	s_mov_b64 s[8:9], 0
	s_cselect_b64 s[6:7], -1, 0
	s_branch .LBB0_355
